# v77 + nt hint on HGRN2's coalesced once-read chunk loads (log-f, q, k rows)
# speedup vs baseline: 1.0126x; 1.0087x over previous
.LBB0_1167:
	s_or_b64 exec, exec, s[0:1]
	s_lshl_b32 s36, s72, 7
	s_ashr_i32 s1, s3, 31
	v_readlane_b32 s0, v251, 10
	s_add_u32 s0, s0, s3
	v_readlane_b32 s3, v251, 11
	s_addc_u32 s1, s3, s1
	s_ashr_i32 s3, s2, 31
	s_lshl_b64 s[6:7], s[36:37], 2
	s_waitcnt lgkmcnt(0)
	s_add_u32 s6, s4, s6
	s_addc_u32 s7, s5, s7
	s_ashr_i32 s5, s8, 31
	s_add_u32 s4, s30, s8
	s_addc_u32 s5, s31, s5
	v_readlane_b32 s8, v254, 15
	s_add_u32 s2, s8, s2
	v_readlane_b32 s8, v254, 16
	v_lshlrev_b32_e32 v74, 1, v18
	s_addc_u32 s3, s8, s3
	v_ashrrev_i32_e32 v75, 31, v74
	v_lshl_add_u64 v[76:77], v[74:75], 2, s[2:3]
	v_readlane_b32 s2, v254, 39
	s_add_u32 s2, s0, s2
	v_readlane_b32 s3, v254, 38
	v_readlane_b32 s8, v254, 14
	s_addc_u32 s3, s1, s3
	s_lshl_b32 s36, s8, 1
	s_add_u32 s2, s2, s36
	s_addc_u32 s3, s3, 0
	v_lshl_add_u64 v[2:3], v[74:75], 1, s[2:3]
	s_mov_b64 s[2:3], 0x2000
	v_lshl_add_u64 v[78:79], v[2:3], 0, s[2:3]
	v_readlane_b32 s2, v254, 42
	v_mov_b64_e32 v[4:5], s[0:1]
	s_movk_i32 s11, 0x4000
	v_add_u32_e32 v6, s2, v18
	v_mad_i64_i32 v[4:5], s[2:3], v6, s28, v[4:5]
	v_add_co_u32_e32 v6, vcc, s66, v2
	s_movk_i32 s3, 0x2000
	s_nop 0
	v_addc_co_u32_e32 v7, vcc, 0, v3, vcc
	v_add_co_u32_e32 v8, vcc, s3, v76
	s_mov_b32 s3, 0x9000
	s_nop 0
	v_addc_co_u32_e32 v9, vcc, 0, v77, vcc
	v_add_co_u32_e32 v10, vcc, s3, v2
	s_mov_b32 s3, 0xf000
	s_nop 0
	v_addc_co_u32_e32 v11, vcc, 0, v3, vcc
	v_add_co_u32_e32 v12, vcc, s11, v76
	v_readlane_b32 s10, v254, 17
	s_nop 0
	v_addc_co_u32_e32 v13, vcc, 0, v77, vcc
	v_add_co_u32_e32 v14, vcc, s3, v2
	s_mov_b32 s3, 0x15000
	s_nop 0
	v_addc_co_u32_e32 v15, vcc, 0, v3, vcc
	v_add_co_u32_e32 v16, vcc, s28, v76
	s_lshl_b32 s8, s10, 1
	s_nop 0
	v_addc_co_u32_e32 v17, vcc, 0, v77, vcc
	v_add_co_u32_e32 v20, vcc, s3, v2
	s_mov_b32 s3, 0x8000
	s_nop 0
	v_addc_co_u32_e32 v21, vcc, 0, v3, vcc
	global_load_dword v75, v[6:7], off offset:-4096 nt
	global_load_dword v125, v[6:7], off nt
	global_load_dword v126, v[10:11], off offset:-4096 nt
	global_load_dword v127, v[10:11], off nt
	global_load_dword v128, v[14:15], off offset:-4096 nt
	global_load_dword v129, v[14:15], off nt
	global_load_dword v130, v[20:21], off offset:-4096 nt
	global_load_dword v131, v[20:21], off nt
	v_add_co_u32_e32 v6, vcc, s3, v76
	s_mov_b32 s3, 0x1b000
	s_nop 0
	v_addc_co_u32_e32 v7, vcc, 0, v77, vcc
	global_load_dwordx2 v[80:81], v[8:9], off nt
	global_load_dwordx2 v[82:83], v[12:13], off nt
	global_load_dwordx2 v[86:87], v[16:17], off nt
	global_load_dwordx2 v[90:91], v[6:7], off nt
	v_add_co_u32_e32 v6, vcc, s3, v2
	s_mov_b32 s3, 0xa000
	s_nop 0
	v_addc_co_u32_e32 v7, vcc, 0, v3, vcc
	v_add_co_u32_e32 v8, vcc, s3, v76
	s_mov_b32 s3, 0x21000
	s_nop 0
	v_addc_co_u32_e32 v9, vcc, 0, v77, vcc
	v_add_co_u32_e32 v10, vcc, s3, v2
	s_mov_b32 s3, 0xc000
	s_nop 0
	v_addc_co_u32_e32 v11, vcc, 0, v3, vcc
	v_add_co_u32_e32 v12, vcc, s3, v76
	s_mov_b32 s3, 0x27000
	s_nop 0
	v_addc_co_u32_e32 v13, vcc, 0, v77, vcc
	v_add_co_u32_e32 v14, vcc, s3, v2
	s_mov_b32 s3, 0xe000
	s_nop 0
	v_addc_co_u32_e32 v15, vcc, 0, v3, vcc
	v_add_co_u32_e32 v16, vcc, s3, v76
	s_mov_b32 s3, 0x2d000
	s_nop 0
	v_addc_co_u32_e32 v17, vcc, 0, v77, vcc
	v_add_co_u32_e32 v2, vcc, s3, v2
	global_load_dwordx2 v[96:97], v[8:9], off nt
	global_load_dwordx2 v[100:101], v[12:13], off nt
	global_load_dwordx2 v[102:103], v[16:17], off nt
	v_addc_co_u32_e32 v3, vcc, 0, v3, vcc
	global_load_dword v140, v[6:7], off offset:-4096 nt
	global_load_dword v142, v[6:7], off nt
	global_load_dword v144, v[10:11], off offset:-4096 nt
	global_load_dword v149, v[10:11], off nt
	global_load_dword v156, v[14:15], off offset:-4096 nt
	global_load_dword v157, v[14:15], off nt
	global_load_dword v158, v[2:3], off offset:-4096 nt
	global_load_dword v159, v[2:3], off nt
	v_lshl_add_u64 v[2:3], v[4:5], 0, s[36:37]
	s_mov_b32 s9, s37
	v_ashrrev_i32_e32 v19, 4, v18
	v_lshl_add_u64 v[2:3], v[2:3], 0, s[8:9]
	s_mov_b64 s[8:9], 0x4000
	v_lshl_add_u64 v[84:85], v[2:3], 0, s[8:9]
	v_add_co_u32_e32 v2, vcc, s11, v2
	v_lshlrev_b32_e32 v88, 2, v19
	s_nop 0
	v_addc_co_u32_e32 v3, vcc, 0, v3, vcc
	v_ashrrev_i32_e32 v89, 31, v88
	v_readlane_b32 s8, v254, 47
	global_load_dwordx4 v[22:25], v[2:3], off
	global_load_dwordx2 v[92:93], v[76:77], off nt
	global_load_dwordx4 v[26:29], v[84:85], off offset:16
	v_lshl_add_u64 v[2:3], v[88:89], 2, s[6:7]
	s_lshl_b32 s6, s8, 2
	s_mov_b32 s7, s37
	v_lshl_add_u64 v[14:15], v[2:3], 0, s[6:7]
	global_load_dwordx4 v[2:5], v[14:15], off
	global_load_dwordx4 v[6:9], v[14:15], off offset:64
	global_load_dwordx4 v[10:13], v[14:15], off offset:128
	s_nop 0
	global_load_dwordx4 v[14:17], v[14:15], off offset:192
	v_add_u32_e32 v0, 0, v0
	s_movk_i32 s3, 0x11c
	v_mad_u64_u32 v[20:21], s[6:7], v18, s3, v[0:1]
	v_and_b32_e32 v124, 15, v18
	v_readlane_b32 s7, v254, 25
	v_lshlrev_b32_e32 v132, 3, v18
	v_and_b32_e32 v133, -16, v18
	v_readlane_b32 s3, v254, 43
	s_movk_i32 s11, 0x90
	v_cmp_gt_u32_e64 s[86:87], 16, v18
	v_lshl_add_u32 v135, v18, 2, s7
	v_or_b32_e32 v18, s10, v124
	v_or_b32_e32 v30, s3, v124
	v_mul_lo_u32 v18, v18, s11
	v_mul_lo_u32 v31, v30, s11
	s_add_i32 s3, 0, 0x15c00
	s_add_i32 s6, 0, 0x18000
	v_add_u32_e32 v34, 0, v18
	v_add_u32_e32 v18, s10, v88
	v_sub_u32_e32 v21, v124, v88
	v_add_u32_e32 v31, s3, v31
	s_add_i32 s3, 0, 0x11400
	v_lshlrev_b32_e32 v35, 2, v18
	v_lshl_add_u32 v36, v18, 1, s6
	v_or_b32_e32 v18, s8, v124
	v_add_u32_e32 v32, s3, v133
	v_cmp_gt_i32_e64 s[88:89], 0, v21
	v_cmp_gt_i32_e64 s[90:91], 1, v21
	v_cmp_gt_i32_e64 s[92:93], 2, v21
	v_cmp_gt_i32_e64 s[94:95], 3, v21
	v_mul_u32_u24_e32 v21, 0x90, v18
	v_mul_u32_u24_e32 v37, 0x110, v18
	v_mov_b32_e32 v18, s3
	v_readlane_b32 s3, v254, 44
	v_mul_lo_u32 v30, v30, s29
	v_mad_u32_u24 v137, v124, s11, v18
	v_or_b32_e32 v138, s3, v124
	v_readlane_b32 s3, v255, 9
	v_readlane_b32 s9, v254, 48
	v_add_u32_e32 v30, 0, v30
	v_add_u32_e32 v33, s6, v133
	v_readlane_b32 s7, v254, 24
	v_add_u32_e32 v38, 0x1200, v137
	v_add_u32_e32 v39, 0x2400, v137
	v_add_u32_e32 v40, 0x3600, v137
	v_add_u32_e32 v94, s8, v88
	v_mul_u32_u24_e32 v41, 0x110, v124
	v_lshl_add_u32 v139, v19, 3, s3
	v_readlane_b32 s3, v255, 10
	v_mov_b32_e32 v18, 0
	v_add_u32_e32 v19, 0, v35
	s_mov_b32 s2, 0
	v_add_u32_e32 v134, 0, v133
	v_lshl_add_u32 v136, v124, 2, s7
	v_ashrrev_i32_e32 v95, 31, v94
	v_lshl_add_u64 v[98:99], v[88:89], 0, s[8:9]
	v_add3_u32 v141, v41, v133, s3
	v_add_u32_e32 v143, s10, v20
	v_add_u32_e32 v145, v31, v133
	v_add_u32_e32 v146, v30, v133
	v_add_u32_e32 v147, v32, v21
	v_add_u32_e32 v148, v33, v37
	v_add_u32_e32 v150, v34, v133
	v_add_u32_e32 v151, 0x20800, v19
	v_add_u32_e32 v152, v38, v133
	v_add_u32_e32 v153, v39, v133
	v_add_u32_e32 v154, v40, v133
	v_add_u32_e32 v155, v36, v41
	v_mov_b32_e32 v19, v18
	v_mov_b32_e32 v20, v18
	v_mov_b32_e32 v21, v18
	v_mov_b32_e32 v30, v18
	v_mov_b32_e32 v31, v18
	v_mov_b32_e32 v32, v18
	v_mov_b32_e32 v33, v18
	v_mov_b32_e32 v34, v18
	v_mov_b32_e32 v35, v18
	v_mov_b32_e32 v36, v18
	v_mov_b32_e32 v37, v18
	v_mov_b32_e32 v38, v18
	v_mov_b32_e32 v39, v18
	v_mov_b32_e32 v40, v18
	v_mov_b32_e32 v41, v18
	v_mov_b32_e32 v42, v18
	v_mov_b32_e32 v43, v18
	v_mov_b32_e32 v44, v18
	v_mov_b32_e32 v45, v18
	v_mov_b32_e32 v50, v18
	v_mov_b32_e32 v51, v18
	v_mov_b32_e32 v52, v18
	v_mov_b32_e32 v53, v18
	v_mov_b32_e32 v46, v18
	v_mov_b32_e32 v47, v18
	v_mov_b32_e32 v48, v18
	v_mov_b32_e32 v49, v18
	v_mov_b32_e32 v54, v18
	v_mov_b32_e32 v55, v18
	v_mov_b32_e32 v56, v18
	v_mov_b32_e32 v57, v18
	s_barrier
	s_branch .LBB0_1169

.LBB0_1173:
	v_readlane_b32 s6, v254, 18
	v_readlane_b32 s7, v254, 19
	s_mul_i32 s3, s20, 0x880
	s_nop 0
	v_cndmask_b32_e64 v123, v123, 0, s[6:7]
	v_cndmask_b32_e64 v122, v122, 0, s[6:7]
	v_readlane_b32 s6, v254, 26
	v_pk_add_f32 v[72:73], v[72:73], v[122:123]
	v_readlane_b32 s7, v254, 27
	s_nop 1
	v_cndmask_b32_e64 v73, v123, v73, s[6:7]
	v_cndmask_b32_e64 v72, v122, v72, s[6:7]
	v_readlane_b32 s6, v254, 28
	v_pk_add_f32 v[66:67], v[66:67], v[72:73]
	v_readlane_b32 s7, v254, 29
	s_nop 1
	v_cndmask_b32_e64 v67, v73, v67, s[6:7]
	v_cndmask_b32_e64 v66, v72, v66, s[6:7]
	v_readlane_b32 s6, v254, 30
	v_pk_add_f32 v[68:69], v[68:69], v[66:67]
	v_readlane_b32 s7, v254, 31
	s_nop 1
	v_cndmask_b32_e64 v67, v67, v69, s[6:7]
	v_cndmask_b32_e64 v66, v66, v68, s[6:7]
	v_readlane_b32 s6, v254, 32
	v_pk_add_f32 v[62:63], v[62:63], v[66:67]
	v_readlane_b32 s7, v254, 33
	v_and_b32_e32 v69, 0xffff0000, v125
	v_lshlrev_b32_e32 v68, 16, v125
	v_cndmask_b32_e64 v63, v67, v63, s[6:7]
	v_cndmask_b32_e64 v62, v66, v62, s[6:7]
	v_readlane_b32 s6, v254, 34
	v_pk_add_f32 v[64:65], v[64:65], v[62:63]
	v_readlane_b32 s7, v254, 35
	v_lshlrev_b32_e32 v66, 16, v75
	v_and_b32_e32 v67, 0xffff0000, v75
	v_cndmask_b32_e64 v63, v63, v65, s[6:7]
	v_cndmask_b32_e64 v62, v62, v64, s[6:7]
	v_readlane_b32 s6, v254, 36
	v_pk_add_f32 v[58:59], v[58:59], v[62:63]
	v_readlane_b32 s7, v254, 37
	s_nop 1
	v_cndmask_b32_e64 v59, v63, v59, s[6:7]
	v_cndmask_b32_e64 v58, v62, v58, s[6:7]
	v_readlane_b32 s6, v254, 40
	v_pk_add_f32 v[60:61], v[60:61], v[58:59]
	v_readlane_b32 s7, v254, 41
	s_nop 1
	v_cndmask_b32_e64 v58, v58, v60, s[6:7]
	v_sub_f32_e32 v60, v120, v70
	v_cndmask_b32_e64 v59, v59, v61, s[6:7]
	v_exp_f32_e32 v64, v60
	v_sub_f32_e32 v60, v121, v71
	v_exp_f32_e32 v65, v60
	v_pk_add_f32 v[60:61], v[118:119], v[58:59]
	s_nop 0
	v_pk_add_f32 v[62:63], v[60:61], v[70:71] neg_lo:[0,1] neg_hi:[0,1]
	v_exp_f32_e32 v60, v60
	v_min_f32_e32 v73, 0x42e60000, v63
	v_min_f32_e64 v63, -v63, s14
	v_min_f32_e32 v72, 0x42e60000, v62
	v_min_f32_e64 v62, -v62, s14
	v_exp_f32_e32 v63, v63
	v_exp_f32_e32 v72, v72
	v_exp_f32_e32 v73, v73
	v_exp_f32_e32 v62, v62
	v_exp_f32_e32 v61, v61
	v_mul_f32_e32 v63, v63, v69
	v_add_u32_e32 v69, s3, v0
	v_mul_f32_e32 v60, v60, v66
	v_mul_f32_e32 v72, v72, v66
	v_mul_f32_e32 v73, v73, v67
	v_mul_f32_e32 v62, v62, v68
	v_cvt_pk_bf16_f32 v68, v72, v73
	ds_write_b32 v69, v68
	v_mul_f32_e32 v61, v61, v67
	v_cvt_pk_bf16_f32 v60, v60, v61
	ds_write_b32 v69, v60 offset:17408
	v_cvt_pk_bf16_f32 v60, v62, v63
	ds_write_b32 v69, v60 offset:34816
	v_pk_add_f32 v[60:61], v[116:117], v[58:59]
	v_mul_f32_e32 v66, v64, v62
	v_mul_f32_e32 v67, v63, v65
	v_pk_add_f32 v[62:63], v[60:61], v[70:71] neg_lo:[0,1] neg_hi:[0,1]
	v_exp_f32_e32 v60, v60
	v_min_f32_e32 v117, 0x42e60000, v62
	v_min_f32_e32 v118, 0x42e60000, v63
	v_min_f32_e64 v62, -v62, s14
	v_exp_f32_e32 v117, v117
	v_exp_f32_e32 v118, v118
	v_exp_f32_e32 v62, v62
	v_min_f32_e64 v63, -v63, s14
	v_exp_f32_e32 v61, v61
	v_exp_f32_e32 v63, v63
	v_lshlrev_b32_e32 v68, 16, v126
	v_and_b32_e32 v72, 0xffff0000, v126
	v_lshlrev_b32_e32 v73, 16, v127
	v_mul_f32_e32 v60, v60, v68
	v_and_b32_e32 v116, 0xffff0000, v127
	v_mul_f32_e32 v117, v117, v68
	v_mul_f32_e32 v118, v118, v72
	v_mul_f32_e32 v62, v62, v73
	v_cvt_pk_bf16_f32 v73, v117, v118
	ds_write_b32 v69, v73 offset:272
	v_mul_f32_e32 v61, v61, v72
	v_cvt_pk_bf16_f32 v60, v60, v61
	v_mul_f32_e32 v63, v63, v116
	ds_write_b32 v69, v60 offset:17680
	v_cvt_pk_bf16_f32 v60, v62, v63
	ds_write_b32 v69, v60 offset:35088
	v_pk_add_f32 v[60:61], v[114:115], v[58:59]
	v_mul_f32_e32 v68, v64, v62
	v_mul_f32_e32 v72, v63, v65
	v_pk_add_f32 v[62:63], v[60:61], v[70:71] neg_lo:[0,1] neg_hi:[0,1]
	v_exp_f32_e32 v60, v60
	v_min_f32_e32 v117, 0x42e60000, v62
	v_min_f32_e32 v118, 0x42e60000, v63
	v_min_f32_e64 v62, -v62, s14
	v_exp_f32_e32 v117, v117
	v_exp_f32_e32 v118, v118
	v_exp_f32_e32 v62, v62
	v_min_f32_e64 v63, -v63, s14
	v_exp_f32_e32 v61, v61
	v_exp_f32_e32 v63, v63
	v_lshlrev_b32_e32 v73, 16, v128
	v_and_b32_e32 v114, 0xffff0000, v128
	v_lshlrev_b32_e32 v115, 16, v129
	v_mul_f32_e32 v60, v60, v73
	v_and_b32_e32 v116, 0xffff0000, v129
	v_mul_f32_e32 v117, v117, v73
	v_mul_f32_e32 v118, v118, v114
	v_mul_f32_e32 v62, v62, v115
	v_cvt_pk_bf16_f32 v115, v117, v118
	ds_write_b32 v69, v115 offset:544
	v_mul_f32_e32 v61, v61, v114
	v_cvt_pk_bf16_f32 v60, v60, v61
	v_mul_f32_e32 v63, v63, v116
	ds_write_b32 v69, v60 offset:17952
	v_cvt_pk_bf16_f32 v60, v62, v63
	ds_write_b32 v69, v60 offset:35360
	v_pk_add_f32 v[60:61], v[112:113], v[58:59]
	v_mul_f32_e32 v73, v64, v62
	v_mul_f32_e32 v114, v63, v65
	v_pk_add_f32 v[62:63], v[60:61], v[70:71] neg_lo:[0,1] neg_hi:[0,1]
	v_exp_f32_e32 v60, v60
	v_min_f32_e32 v117, 0x42e60000, v62
	v_min_f32_e32 v118, 0x42e60000, v63
	v_min_f32_e64 v62, -v62, s14
	v_exp_f32_e32 v117, v117
	v_exp_f32_e32 v118, v118
	v_exp_f32_e32 v62, v62
	v_min_f32_e64 v63, -v63, s14
	v_exp_f32_e32 v61, v61
	v_exp_f32_e32 v63, v63
	v_lshlrev_b32_e32 v112, 16, v130
	v_and_b32_e32 v113, 0xffff0000, v130
	v_lshlrev_b32_e32 v115, 16, v131
	v_mul_f32_e32 v60, v60, v112
	v_and_b32_e32 v116, 0xffff0000, v131
	v_mul_f32_e32 v117, v117, v112
	v_mul_f32_e32 v118, v118, v113
	v_mul_f32_e32 v62, v62, v115
	v_cvt_pk_bf16_f32 v115, v117, v118
	ds_write_b32 v69, v115 offset:816
	v_mul_f32_e32 v61, v61, v113
	v_cvt_pk_bf16_f32 v60, v60, v61
	v_mul_f32_e32 v63, v63, v116
	ds_write_b32 v69, v60 offset:18224
	v_cvt_pk_bf16_f32 v60, v62, v63
	ds_write_b32 v69, v60 offset:35632
	v_pk_add_f32 v[60:61], v[110:111], v[58:59]
	v_mul_f32_e32 v112, v64, v62
	v_mul_f32_e32 v113, v63, v65
	v_pk_add_f32 v[62:63], v[60:61], v[70:71] neg_lo:[0,1] neg_hi:[0,1]
	v_exp_f32_e32 v60, v60
	v_min_f32_e32 v117, 0x42e60000, v62
	v_min_f32_e32 v118, 0x42e60000, v63
	v_min_f32_e64 v62, -v62, s14
	v_exp_f32_e32 v117, v117
	v_exp_f32_e32 v118, v118
	v_exp_f32_e32 v62, v62
	v_min_f32_e64 v63, -v63, s14
	v_exp_f32_e32 v61, v61
	v_exp_f32_e32 v63, v63
	v_lshlrev_b32_e32 v110, 16, v140
	v_and_b32_e32 v111, 0xffff0000, v140
	v_lshlrev_b32_e32 v115, 16, v142
	v_mul_f32_e32 v60, v60, v110
	v_and_b32_e32 v116, 0xffff0000, v142
	v_mul_f32_e32 v117, v117, v110
	v_mul_f32_e32 v118, v118, v111
	v_mul_f32_e32 v62, v62, v115
	v_cvt_pk_bf16_f32 v115, v117, v118
	ds_write_b32 v69, v115 offset:1088
	v_mul_f32_e32 v61, v61, v111
	v_cvt_pk_bf16_f32 v60, v60, v61
	v_mul_f32_e32 v63, v63, v116
	ds_write_b32 v69, v60 offset:18496
	v_cvt_pk_bf16_f32 v60, v62, v63
	ds_write_b32 v69, v60 offset:35904
	v_pk_add_f32 v[60:61], v[108:109], v[58:59]
	v_mul_f32_e32 v110, v64, v62
	v_mul_f32_e32 v111, v63, v65
	v_pk_add_f32 v[62:63], v[60:61], v[70:71] neg_lo:[0,1] neg_hi:[0,1]
	v_exp_f32_e32 v60, v60
	v_min_f32_e32 v117, 0x42e60000, v62
	v_min_f32_e32 v118, 0x42e60000, v63
	v_min_f32_e64 v62, -v62, s14
	v_exp_f32_e32 v117, v117
	v_exp_f32_e32 v118, v118
	v_exp_f32_e32 v62, v62
	v_min_f32_e64 v63, -v63, s14
	v_exp_f32_e32 v61, v61
	v_exp_f32_e32 v63, v63
	v_lshlrev_b32_e32 v108, 16, v144
	v_and_b32_e32 v109, 0xffff0000, v144
	v_lshlrev_b32_e32 v115, 16, v149
	v_mul_f32_e32 v60, v60, v108
	v_and_b32_e32 v116, 0xffff0000, v149
	v_mul_f32_e32 v117, v117, v108
	v_mul_f32_e32 v118, v118, v109
	v_mul_f32_e32 v62, v62, v115
	v_cvt_pk_bf16_f32 v115, v117, v118
	ds_write_b32 v69, v115 offset:1360
	v_mul_f32_e32 v61, v61, v109
	v_cvt_pk_bf16_f32 v60, v60, v61
	v_mul_f32_e32 v63, v63, v116
	ds_write_b32 v69, v60 offset:18768
	v_cvt_pk_bf16_f32 v60, v62, v63
	ds_write_b32 v69, v60 offset:36176
	v_pk_add_f32 v[60:61], v[106:107], v[58:59]
	v_mul_f32_e32 v108, v64, v62
	v_mul_f32_e32 v109, v63, v65
	v_pk_add_f32 v[62:63], v[60:61], v[70:71] neg_lo:[0,1] neg_hi:[0,1]
	v_exp_f32_e32 v60, v60
	v_min_f32_e32 v117, 0x42e60000, v62
	v_min_f32_e32 v118, 0x42e60000, v63
	v_min_f32_e64 v62, -v62, s14
	v_exp_f32_e32 v117, v117
	v_exp_f32_e32 v118, v118
	v_exp_f32_e32 v62, v62
	v_min_f32_e64 v63, -v63, s14
	v_exp_f32_e32 v61, v61
	v_exp_f32_e32 v63, v63
	v_lshlrev_b32_e32 v106, 16, v156
	v_and_b32_e32 v107, 0xffff0000, v156
	v_lshlrev_b32_e32 v115, 16, v157
	v_mul_f32_e32 v60, v60, v106
	v_and_b32_e32 v116, 0xffff0000, v157
	v_mul_f32_e32 v117, v117, v106
	v_mul_f32_e32 v118, v118, v107
	v_mul_f32_e32 v62, v62, v115
	v_cvt_pk_bf16_f32 v115, v117, v118
	ds_write_b32 v69, v115 offset:1632
	v_mul_f32_e32 v61, v61, v107
	v_cvt_pk_bf16_f32 v60, v60, v61
	v_mul_f32_e32 v63, v63, v116
	ds_write_b32 v69, v60 offset:19040
	v_cvt_pk_bf16_f32 v60, v62, v63
	v_pk_add_f32 v[58:59], v[104:105], v[58:59]
	ds_write_b32 v69, v60 offset:36448
	v_pk_add_f32 v[60:61], v[58:59], v[70:71] neg_lo:[0,1] neg_hi:[0,1]
	v_exp_f32_e32 v58, v58
	v_min_f32_e32 v106, 0x42e60000, v60
	v_min_f32_e32 v107, 0x42e60000, v61
	v_min_f32_e64 v60, -v60, s14
	v_exp_f32_e32 v106, v106
	v_exp_f32_e32 v107, v107
	v_exp_f32_e32 v60, v60
	v_min_f32_e64 v61, -v61, s14
	v_exp_f32_e32 v59, v59
	v_exp_f32_e32 v61, v61
	v_lshlrev_b32_e32 v70, 16, v158
	v_and_b32_e32 v71, 0xffff0000, v158
	v_lshlrev_b32_e32 v104, 16, v159
	v_mul_f32_e32 v58, v58, v70
	v_and_b32_e32 v105, 0xffff0000, v159
	v_mul_f32_e32 v106, v106, v70
	v_mul_f32_e32 v107, v107, v71
	v_mul_f32_e32 v60, v60, v104
	v_cvt_pk_bf16_f32 v104, v106, v107
	ds_write_b32 v69, v104 offset:1904
	v_mul_f32_e32 v59, v59, v71
	v_cvt_pk_bf16_f32 v58, v58, v59
	v_mul_f32_e32 v61, v61, v105
	ds_write_b32 v69, v58 offset:19312
	v_cvt_pk_bf16_f32 v58, v60, v61
	ds_write_b32 v69, v58 offset:36720
	v_cvt_pk_bf16_f32 v58, v66, v68
	v_mul_f32_e32 v62, v64, v62
	v_mul_f32_e32 v63, v63, v65
	v_mul_f32_e32 v64, v64, v60
	v_mul_f32_e32 v65, v61, v65
	v_cvt_pk_bf16_f32 v59, v73, v112
	v_cvt_pk_bf16_f32 v60, v110, v108
	v_cvt_pk_bf16_f32 v61, v62, v64
	ds_write_b128 v143, v[58:61] offset:52224
	v_cvt_pk_bf16_f32 v58, v67, v72
	s_add_i32 s3, s2, 1
	v_cvt_pk_bf16_f32 v59, v114, v113
	v_cvt_pk_bf16_f32 v60, v111, v109
	v_cvt_pk_bf16_f32 v61, v63, v65
	ds_write_b128 v143, v[58:61] offset:52368
	v_add_u32_e32 v58, s19, v74
	s_cmp_eq_u32 s2, 31
	ds_write_b16 v58, v22
	ds_write_b16_d16_hi v58, v22 offset:144
	ds_write_b16 v58, v23 offset:288
	ds_write_b16_d16_hi v58, v23 offset:432
	ds_write_b16 v58, v24 offset:576
	ds_write_b16_d16_hi v58, v24 offset:720
	ds_write_b16 v58, v25 offset:864
	ds_write_b16_d16_hi v58, v25 offset:1008
	s_waitcnt vmcnt(4)
	ds_write_b16 v58, v26 offset:1152
	ds_write_b16_d16_hi v58, v26 offset:1296
	ds_write_b16 v58, v27 offset:1440
	ds_write_b16_d16_hi v58, v27 offset:1584
	ds_write_b16 v58, v28 offset:1728
	ds_write_b16_d16_hi v58, v28 offset:1872
	ds_write_b16 v58, v29 offset:2016
	ds_write_b16_d16_hi v58, v29 offset:2160
	s_cbranch_scc1 .LBB0_1175
	s_lshl_b32 s6, s3, 6
	s_mov_b32 s7, s37
	s_lshl_b64 s[8:9], s[6:7], 13
	v_lshl_add_u64 v[22:23], v[76:77], 0, s[8:9]
	v_mad_u64_u32 v[24:25], s[8:9], s6, v204, v[78:79]
	s_or_b32 s8, s6, 1
	s_mov_b32 s9, s37
	v_add_co_u32_e32 v26, vcc, 0x1000, v24
	s_lshl_b64 s[10:11], s[8:9], 13
	s_nop 0
	v_addc_co_u32_e32 v27, vcc, 0, v25, vcc
	v_lshl_add_u64 v[28:29], v[76:77], 0, s[10:11]
	global_load_dwordx2 v[92:93], v[22:23], off nt
	global_load_dword v75, v[24:25], off nt
	global_load_dword v125, v[26:27], off nt
	global_load_dwordx2 v[80:81], v[28:29], off nt
	v_mad_u64_u32 v[22:23], s[8:9], s8, v204, v[78:79]
	v_add_co_u32_e32 v24, vcc, 0x1000, v22
	s_or_b32 s8, s6, 2
	s_mov_b32 s9, s37
	v_addc_co_u32_e32 v25, vcc, 0, v23, vcc
	s_lshl_b64 s[10:11], s[8:9], 13
	v_mad_u64_u32 v[28:29], s[8:9], s8, v204, v[78:79]
	v_add_co_u32_e32 v58, vcc, 0x1000, v28
	s_or_b32 s8, s6, 3
	s_mov_b32 s9, s37
	v_lshl_add_u64 v[26:27], v[76:77], 0, s[10:11]
	v_addc_co_u32_e32 v59, vcc, 0, v29, vcc
	global_load_dword v126, v[22:23], off nt
	global_load_dword v127, v[24:25], off nt
	global_load_dwordx2 v[82:83], v[26:27], off nt
	global_load_dword v128, v[28:29], off nt
	global_load_dword v129, v[58:59], off nt
	s_lshl_b64 s[10:11], s[8:9], 13
	v_mad_u64_u32 v[24:25], s[8:9], s8, v204, v[78:79]
	s_or_b32 s8, s6, 4
	s_mov_b32 s9, s37
	v_lshl_add_u64 v[22:23], v[76:77], 0, s[10:11]
	v_add_co_u32_e32 v26, vcc, 0x1000, v24
	s_lshl_b64 s[10:11], s[8:9], 13
	s_nop 0
	v_addc_co_u32_e32 v27, vcc, 0, v25, vcc
	v_lshl_add_u64 v[28:29], v[76:77], 0, s[10:11]
	global_load_dwordx2 v[86:87], v[22:23], off nt
	global_load_dword v130, v[24:25], off nt
	global_load_dword v131, v[26:27], off nt
	global_load_dwordx2 v[90:91], v[28:29], off nt
	v_mad_u64_u32 v[22:23], s[8:9], s8, v204, v[78:79]
	v_add_co_u32_e32 v24, vcc, 0x1000, v22
	s_or_b32 s8, s6, 5
	s_mov_b32 s9, s37
	v_addc_co_u32_e32 v25, vcc, 0, v23, vcc
	s_lshl_b64 s[10:11], s[8:9], 13
	v_mad_u64_u32 v[28:29], s[8:9], s8, v204, v[78:79]
	v_add_co_u32_e32 v58, vcc, 0x1000, v28
	s_or_b32 s8, s6, 6
	s_mov_b32 s9, s37
	v_lshl_add_u64 v[26:27], v[76:77], 0, s[10:11]
	v_addc_co_u32_e32 v59, vcc, 0, v29, vcc
	global_load_dword v140, v[22:23], off nt
	global_load_dword v142, v[24:25], off nt
	global_load_dwordx2 v[96:97], v[26:27], off nt
	global_load_dword v144, v[28:29], off nt
	global_load_dword v149, v[58:59], off nt
	s_lshl_b64 s[10:11], s[8:9], 13
	v_mad_u64_u32 v[24:25], s[8:9], s8, v204, v[78:79]
	s_or_b32 s6, s6, 7
	v_lshl_add_u64 v[22:23], v[76:77], 0, s[10:11]
	v_add_co_u32_e32 v26, vcc, 0x1000, v24
	s_lshl_b64 s[8:9], s[6:7], 13
	s_nop 0
	v_addc_co_u32_e32 v27, vcc, 0, v25, vcc
	v_lshl_add_u64 v[28:29], v[76:77], 0, s[8:9]
	global_load_dwordx2 v[100:101], v[22:23], off nt
	global_load_dword v156, v[24:25], off nt
	global_load_dword v157, v[26:27], off nt
	global_load_dwordx2 v[102:103], v[28:29], off nt
	v_mad_u64_u32 v[22:23], s[6:7], s6, v204, v[78:79]
	v_add_co_u32_e32 v24, vcc, 0x1000, v22
	s_mul_i32 s6, s3, 0x180000
	s_mov_b32 s7, s37
	v_addc_co_u32_e32 v25, vcc, 0, v23, vcc
	v_lshl_add_u64 v[26:27], v[84:85], 0, s[6:7]
	global_load_dword v158, v[22:23], off nt
	global_load_dword v159, v[24:25], off nt
	s_nop 0
	global_load_dwordx4 v[22:25], v[26:27], off
	s_nop 0
	global_load_dwordx4 v[26:29], v[26:27], off offset:16
